# adds P7 chunk-out: gw/gb loads hoisted before next-item prefetch, counted vmcnt so the prefetch stays in flight (a1+a2+raw+prm+q+p7)
# speedup vs baseline: 1.0053x; 1.0053x over previous
; #define LAS __attribute__((address_space(3)))
; __device__ __forceinline__ unsigned f2bf(float f) { return pk2(f, 0.f) & 0xffffu; }
; #define LBAR() asm volatile("s_waitcnt lgkmcnt(0)\n\ts_barrier" ::: "memory")
; __device__ __forceinline__ void rwkv_chunk_out_all(Frame& F) {
;     ...
;         for (int q = 0; q < 2; ++q) { const int tw = 2 * w + q, p0 = 16 * (tw >> 2), q0 = 16 * (tw & 3);
;             f32x4 a = (f32x4){bflo(cur.y0[q].x), bfhi(cur.y0[q].x), bflo(cur.y0[q].y), bfhi(cur.y0[q].y)};
; #pragma unroll
;             for (int k = 0; k < 2; ++k) a = __builtin_amdgcn_mfma_f32_16x16x32_bf16(cur.sf[q][k], cur.rf[q][k], a, 0, 0, 0);
; #pragma unroll
;             for (int v = 0; v < 4; ++v) *(LAS float*)(L + L_YL + ((p0 + fr) * 65 + q0 + 4 * fq + v) * 4) = a[v];
;         }
;         LBAR();
;         {
;             const float gw = (PRM + 4608)[gc], gb = (PRM + 5120)[gc];
;             bf16* YM = (bf16*)(F.ws + WS_YMIX);
;             float yv[8], sm[8], sv[8];
; #pragma unroll
;             for (int tt = 0; tt < 8; ++tt) { yv[tt] = *(const LAS float*)(L + L_YL + ((8 * w + tt) * 65 + ch) * 4); sm[tt] = yv[tt]; }
;             wave_sum8(sm);
; #pragma unroll
;             for (int tt = 0; tt < 8; ++tt) { yv[tt] -= sm[tt] * (1.f / 64.f); sv[tt] = yv[tt] * yv[tt]; }
;             wave_sum8(sv);
; #pragma unroll
;             for (int tt = 0; tt < 8; ++tt) { const int t = 8 * w + tt;
;                 const float yn = yv[tt] * __builtin_amdgcn_rsqf(sv[tt] * (1.f / 64.f) + GN_EPS) * gw + gb;
;                 const float o = (yn + ((tt & 1) ? bfhi(vbq[tt >> 1]) : bflo(vbq[tt >> 1]))) * ((tt & 1) ? bfhi(ggq[tt >> 1]) : bflo(ggq[tt >> 1]));
;                 YM[(size_t)(row0 + t) * D + gc] = (bf16)f2bf(o); }
.Lp7_body:
	v_lshlrev_b32_e32 v92, 16, v76
	v_and_b32_e32 v93, 0xffff0000, v76
	v_lshlrev_b32_e32 v94, 16, v77
	v_and_b32_e32 v95, 0xffff0000, v77
	s_lshr_b32 s7, s11, 26
	s_add_i32 s7, s10, s7
	v_mfma_f32_16x16x32_bf16 v[52:55], v[52:55], v[36:39], v[92:95]
	s_ashr_i32 s7, s7, 6
	s_lshr_b32 s11, s11, 23
	s_add_i32 s10, s10, s11
	v_mfma_f32_16x16x32_bf16 v[48:51], v[48:51], v[32:35], v[52:55]
	s_lshr_b32 s11, s7, 29
	s_add_i32 s11, s7, s11
	s_and_b32 s11, s11, 0x3fffff8
	s_nop 0
	v_lshlrev_b32_e32 v52, 16, v74
	v_and_b32_e32 v53, 0xffff0000, v74
	v_lshlrev_b32_e32 v54, 16, v75
	v_and_b32_e32 v55, 0xffff0000, v75
	s_sub_i32 s11, s7, s11
	ds_write2_b32 v79, v48, v49 offset1:1
	ds_write2_b32 v79, v50, v51 offset0:2 offset1:3
	v_mfma_f32_16x16x32_bf16 v[36:39], v[44:47], v[36:39], v[52:55]
	v_lshl_add_u32 v44, s11, 6, v208
	v_ashrrev_i32_e32 v45, 31, v44
	s_lshl_b32 s10, s10, 3
	v_mfma_f32_16x16x32_bf16 v[32:35], v[40:43], v[32:35], v[36:39]
	s_nop 7
	ds_write2_b32 v80, v32, v33 offset1:1
	ds_write2_b32 v80, v34, v35 offset0:2 offset1:3
	v_lshlrev_b64 v[32:33], 2, v[44:45]
	s_waitcnt lgkmcnt(0)
	s_barrier
	v_lshl_add_u64 v[34:35], s[0:1], 0, v[32:33]
	v_lshl_add_u64 v[32:33], s[2:3], 0, v[32:33]
	v_mov_b32_e32 v36, v100
	v_mov_b32_e32 v37, v101
	v_add_u32_e32 v32, 0, v78
	ds_read_b32 v34, v32
	ds_read_b32 v38, v81
	ds_read_b32 v39, v82
	ds_read_b32 v40, v84
	ds_read_b32 v41, v83
	ds_read_b32 v42, v85
	ds_read_b32 v43, v86
	ds_read_b32 v46, v87
	s_waitcnt lgkmcnt(4)
	v_mov_b32_e32 v32, v40
	v_mov_b32_e32 v33, v34
	s_nop 1
	v_permlane32_swap_b32_e32 v33, v32
	v_add_f32_e32 v32, v33, v32
	s_waitcnt lgkmcnt(2)
	v_mov_b32_e32 v33, v42
	v_mov_b32_e32 v35, v38
	s_nop 1
	v_permlane32_swap_b32_e32 v35, v33
	v_add_f32_e32 v33, v35, v33
	v_mov_b32_e32 v35, v39
	s_waitcnt lgkmcnt(1)
	v_mov_b32_e32 v47, v43
	s_nop 1
	v_permlane32_swap_b32_e32 v35, v47
	v_add_f32_e32 v35, v35, v47
	s_nop 1
	v_permlane16_swap_b32_e32 v32, v35
	v_add_f32_e32 v32, v32, v35
	v_mov_b32_e32 v47, v41
	s_waitcnt lgkmcnt(0)
	v_mov_b32_e32 v48, v46
	v_add_f32_dpp v32, v32, v32 quad_perm:[1,0,3,2] row_mask:0xf bank_mask:0xf bound_ctrl:1
	s_nop 0
	v_permlane32_swap_b32_e32 v47, v48
	v_add_f32_dpp v32, v32, v32 quad_perm:[2,3,0,1] row_mask:0xf bank_mask:0xf bound_ctrl:1
	v_add_f32_e32 v47, v47, v48
	s_nop 1
	v_permlane16_swap_b32_e32 v33, v47
	v_add_f32_dpp v32, v32, v32 row_half_mirror row_mask:0xf bank_mask:0xf bound_ctrl:1
	v_add_f32_e32 v33, v33, v47
	s_and_b32 s10, s10, 0xfffff000
	v_add_f32_dpp v32, v32, v32 row_mirror row_mask:0xf bank_mask:0xf bound_ctrl:1
	v_add_f32_dpp v33, v33, v33 quad_perm:[1,0,3,2] row_mask:0xf bank_mask:0xf bound_ctrl:1
	v_readlane_b32 s11, v32, 0
	v_readlane_b32 s14, v32, 16
	v_readlane_b32 s15, v32, 32
	v_readlane_b32 s16, v32, 48
	v_fmac_f32_e32 v34, s11, v89
	v_fmac_f32_e32 v39, s14, v89
	v_fmac_f32_e32 v40, s15, v89
	v_fmac_f32_e32 v43, s16, v89
	v_mul_f32_e32 v32, v34, v34
	v_mul_f32_e32 v35, v39, v39
	v_mul_f32_e32 v48, v40, v40
	v_mul_f32_e32 v50, v43, v43
	s_nop 0
	v_permlane32_swap_b32_e32 v32, v48
	v_permlane32_swap_b32_e32 v35, v50
	v_add_f32_e32 v32, v32, v48
	v_add_f32_e32 v35, v35, v50
	s_nop 1
	v_permlane16_swap_b32_e32 v32, v35
	v_add_f32_dpp v33, v33, v33 quad_perm:[2,3,0,1] row_mask:0xf bank_mask:0xf bound_ctrl:1
	v_add_f32_e32 v32, v32, v35
	s_lshl_b32 s7, s7, 12
	v_add_f32_dpp v33, v33, v33 row_half_mirror row_mask:0xf bank_mask:0xf bound_ctrl:1
	v_add_f32_dpp v32, v32, v32 quad_perm:[1,0,3,2] row_mask:0xf bank_mask:0xf bound_ctrl:1
	s_sub_i32 s7, s10, s7
	v_add_f32_dpp v33, v33, v33 row_mirror row_mask:0xf bank_mask:0xf bound_ctrl:1
	v_add_f32_dpp v32, v32, v32 quad_perm:[2,3,0,1] row_mask:0xf bank_mask:0xf bound_ctrl:1
	v_readlane_b32 s17, v33, 0
	v_readlane_b32 s18, v33, 16
	v_readlane_b32 s19, v33, 32
	v_readlane_b32 s20, v33, 48
	v_add_f32_dpp v32, v32, v32 row_half_mirror row_mask:0xf bank_mask:0xf bound_ctrl:1
	v_fmac_f32_e32 v38, s17, v89
	v_fmac_f32_e32 v41, s18, v89
	v_fmac_f32_e32 v42, s19, v89
	v_fmac_f32_e32 v46, s20, v89
	v_add_f32_dpp v32, v32, v32 row_mirror row_mask:0xf bank_mask:0xf bound_ctrl:1
	v_mul_f32_e32 v33, v38, v38
	v_mul_f32_e32 v47, v41, v41
	v_mul_f32_e32 v49, v42, v42
	v_mul_f32_e32 v51, v46, v46
	v_readlane_b32 s11, v32, 0
	v_permlane32_swap_b32_e32 v33, v49
	v_permlane32_swap_b32_e32 v47, v51
	v_readlane_b32 s16, v32, 16
	v_readlane_b32 s17, v32, 32
	v_readlane_b32 s18, v32, 48
	v_fma_f32 v32, s11, v90, v88
	v_add_f32_e32 v33, v33, v49
	v_add_f32_e32 v47, v47, v51
	v_rsq_f32_e32 v35, v32
	s_nop 0
	v_permlane16_swap_b32_e32 v33, v47
	v_add_f32_e32 v33, v33, v47
	v_mul_f32_e32 v34, v34, v35
	v_fma_f32 v34, v36, v34, v37
	v_add_f32_dpp v33, v33, v33 quad_perm:[1,0,3,2] row_mask:0xf bank_mask:0xf bound_ctrl:1
	v_lshlrev_b32_e32 v35, 16, v28
	v_add_f32_e32 v34, v34, v35
	v_add_f32_dpp v33, v33, v33 quad_perm:[2,3,0,1] row_mask:0xf bank_mask:0xf bound_ctrl:1
	v_lshlrev_b32_e32 v35, 16, v24
	v_mul_f32_e32 v34, v34, v35
	v_add_f32_dpp v33, v33, v33 row_half_mirror row_mask:0xf bank_mask:0xf bound_ctrl:1
	s_add_i32 s10, s12, s7
	s_add_i32 s14, s10, -7
	v_add_f32_dpp v33, v33, v33 row_mirror row_mask:0xf bank_mask:0xf bound_ctrl:1
	s_ashr_i32 s15, s14, 31
	v_readlane_b32 s19, v33, 0
	v_readlane_b32 s20, v33, 16
	v_readlane_b32 s21, v33, 32
	v_readlane_b32 s22, v33, 48
; #define GAS __attribute__((address_space(1)))
; __device__ __forceinline__ unsigned f2bf(float f) { return pk2(f, 0.f) & 0xffffu; }
; #define LBAR() asm volatile("s_waitcnt lgkmcnt(0)\n\ts_barrier" ::: "memory")
; __device__ __forceinline__ void rwkv_chunk_out_all(Frame& F) {
;     ...
;     for (; item < NITEM; item += F.G) {
;         const int bh = item / NCH, c = item % NCH, b = bh / RW_H, h = bh % RW_H; const int row0 = b * T + c * CH;
;         const int ch = lane, gc = h * 64 + ch;
;         const bf16* VB = (const bf16*)(F.ws + WS_VB) + (size_t)item * 4096; const bf16* G = (const bf16*)(F.ws + WS_G) + (size_t)item * 4096;
;         const v4u vbq = *(const GAS v4u*)(VB + ch * 64 + 8 * w), ggq = *(const GAS v4u*)(G + ch * 64 + 8 * w);
;         const int inext = item + F.G;
;         if (inext < NITEM) chunk_out_load(F, inext, nxt, w, fr, fq);
;     ...
;             for (int tt = 0; tt < 8; ++tt) { const int t = 8 * w + tt;
;                 const float yn = yv[tt] * __builtin_amdgcn_rsqf(sv[tt] * (1.f / 64.f) + GN_EPS) * gw + gb;
;                 const float o = (yn + ((tt & 1) ? bfhi(vbq[tt >> 1]) : bflo(vbq[tt >> 1]))) * ((tt & 1) ? bfhi(ggq[tt >> 1]) : bflo(ggq[tt >> 1]));
;                 YM[(size_t)(row0 + t) * D + gc] = (bf16)f2bf(o); }
;         }
;         LBAR();
;         cur = nxt;
	v_lshl_add_u64 v[32:33], v[44:45], 1, s[4:5]
	v_cvt_pk_bf16_f32 v44, v34, s0
	v_fma_f32 v34, s19, v90, v88
	v_rsq_f32_e32 v45, v34
	s_lshl_b64 s[14:15], s[14:15], 11
	v_lshl_add_u64 v[34:35], v[32:33], 0, s[14:15]
	global_store_short v[34:35], v44, off
	v_mul_f32_e32 v34, v38, v45
	v_fma_f32 v34, v36, v34, v37
	v_and_b32_e32 v28, 0xffff0000, v28
	v_add_f32_e32 v28, v34, v28
	v_and_b32_e32 v24, 0xffff0000, v24
	v_mul_f32_e32 v24, v28, v24
	v_fma_f32 v28, s16, v90, v88
	s_add_i32 s14, s10, -6
	v_rsq_f32_e32 v28, v28
	s_ashr_i32 s15, s14, 31
	s_lshl_b64 s[14:15], s[14:15], 11
	v_cvt_pk_bf16_f32 v24, v24, s0
	v_lshl_add_u64 v[34:35], v[32:33], 0, s[14:15]
	global_store_short v[34:35], v24, off
	v_mul_f32_e32 v24, v39, v28
	v_fma_f32 v24, v36, v24, v37
	v_lshlrev_b32_e32 v28, 16, v29
	v_add_f32_e32 v24, v24, v28
	v_lshlrev_b32_e32 v28, 16, v25
	v_mul_f32_e32 v24, v24, v28
	v_fma_f32 v28, s20, v90, v88
	s_add_i32 s14, s10, -5
	v_rsq_f32_e32 v28, v28
	s_ashr_i32 s15, s14, 31
	s_lshl_b64 s[14:15], s[14:15], 11
	v_cvt_pk_bf16_f32 v24, v24, s0
	v_lshl_add_u64 v[34:35], v[32:33], 0, s[14:15]
	global_store_short v[34:35], v24, off
	v_mul_f32_e32 v24, v41, v28
	v_fma_f32 v24, v36, v24, v37
	v_and_b32_e32 v28, 0xffff0000, v29
	v_add_f32_e32 v24, v24, v28
	v_and_b32_e32 v25, 0xffff0000, v25
	v_mul_f32_e32 v24, v24, v25
	v_cvt_pk_bf16_f32 v28, v24, s0
	v_fma_f32 v24, s17, v90, v88
	s_add_i32 s14, s10, -4
	v_rsq_f32_e32 v29, v24
	s_ashr_i32 s15, s14, 31
	s_lshl_b64 s[14:15], s[14:15], 11
	v_lshl_add_u64 v[24:25], v[32:33], 0, s[14:15]
	global_store_short v[24:25], v28, off
	v_mul_f32_e32 v24, v40, v29
	v_fma_f32 v24, v36, v24, v37
	v_lshlrev_b32_e32 v25, 16, v30
	v_add_f32_e32 v24, v24, v25
	v_lshlrev_b32_e32 v25, 16, v26
	v_mul_f32_e32 v24, v24, v25
	v_cvt_pk_bf16_f32 v28, v24, s0
	v_fma_f32 v24, s21, v90, v88
	s_add_i32 s14, s10, -3
	v_rsq_f32_e32 v29, v24
	s_ashr_i32 s15, s14, 31
	s_lshl_b64 s[14:15], s[14:15], 11
	v_lshl_add_u64 v[24:25], v[32:33], 0, s[14:15]
	global_store_short v[24:25], v28, off
	v_mul_f32_e32 v24, v42, v29
	v_fma_f32 v24, v36, v24, v37
	v_and_b32_e32 v25, 0xffff0000, v30
	v_add_f32_e32 v24, v24, v25
	v_and_b32_e32 v25, 0xffff0000, v26
	v_mul_f32_e32 v24, v24, v25
	v_cvt_pk_bf16_f32 v26, v24, s0
	v_fma_f32 v24, s18, v90, v88
	s_add_i32 s14, s10, -2
	v_rsq_f32_e32 v28, v24
	s_ashr_i32 s15, s14, 31
	s_lshl_b64 s[14:15], s[14:15], 11
	v_lshl_add_u64 v[24:25], v[32:33], 0, s[14:15]
	global_store_short v[24:25], v26, off
	v_mul_f32_e32 v24, v43, v28
	v_fma_f32 v24, v36, v24, v37
	v_lshlrev_b32_e32 v25, 16, v31
	v_add_f32_e32 v24, v24, v25
	v_lshlrev_b32_e32 v25, 16, v27
	v_mul_f32_e32 v24, v24, v25
	v_cvt_pk_bf16_f32 v26, v24, s0
	v_fma_f32 v24, s22, v90, v88
	s_add_i32 s14, s10, -1
	v_rsq_f32_e32 v28, v24
	s_ashr_i32 s15, s14, 31
	s_lshl_b64 s[14:15], s[14:15], 11
	v_lshl_add_u64 v[24:25], v[32:33], 0, s[14:15]
	global_store_short v[24:25], v26, off
	v_mul_f32_e32 v24, v46, v28
	v_fmac_f32_e32 v37, v36, v24
	v_and_b32_e32 v24, 0xffff0000, v31
	v_add_f32_e32 v24, v37, v24
	v_and_b32_e32 v25, 0xffff0000, v27
	s_ashr_i32 s11, s10, 31
	v_mul_f32_e32 v24, v24, v25
	s_lshl_b64 s[10:11], s[10:11], 11
	v_cvt_pk_bf16_f32 v26, v24, s0
	v_lshl_add_u64 v[24:25], v[32:33], 0, s[10:11]
	global_store_short v[24:25], v26, off
	s_waitcnt lgkmcnt(0)
	s_barrier
	s_waitcnt vmcnt(0)
	v_mov_b64_e32 v[34:35], v[14:15]
	v_mov_b64_e32 v[38:39], v[10:11]
	v_mov_b64_e32 v[42:43], v[22:23]
	v_mov_b64_e32 v[46:47], v[18:19]
	v_mov_b64_e32 v[50:51], v[6:7]
	v_mov_b64_e32 v[54:55], v[2:3]
	s_add_i32 s12, s12, s13
	s_andn2_b64 vcc, exec, s[8:9]
	v_mov_b64_e32 v[32:33], v[12:13]
	v_mov_b64_e32 v[36:37], v[8:9]
	v_mov_b64_e32 v[40:41], v[20:21]
	v_mov_b64_e32 v[44:45], v[16:17]
	v_mov_b64_e32 v[48:49], v[4:5]
	v_mov_b64_e32 v[52:53], v[0:1]
	v_mov_b64_e32 v[74:75], v[72:73]
	v_mov_b64_e32 v[76:77], v[70:71]
	s_mov_b32 s10, s6
	s_cbranch_vccz .LBB0_1679
.LBB0_1677:
	s_ashr_i32 s11, s10, 31
	s_lshl_b64 s[6:7], s[10:11], 13
	v_lshl_add_u64 v[92:93], v[58:59], 0, s[6:7]
	v_lshl_add_u64 v[94:95], v[60:61], 0, s[6:7]
	global_load_dwordx4 v[28:31], v[92:93], off
	global_load_dwordx4 v[24:27], v[94:95], off
	s_lshr_b32 s99, s10, 6
	s_and_b32 s99, s99, 7
	s_lshl_b32 s99, s99, 6
	v_add_lshl_u32 v96, v208, s99, 2
	v_mov_b32_e32 v97, 0
	v_lshl_add_u64 v[98:99], s[0:1], 0, v[96:97]
	v_lshl_add_u64 v[96:97], s[2:3], 0, v[96:97]
	global_load_dword v100, v[98:99], off
	global_load_dword v101, v[96:97], off
	s_add_i32 s6, s10, s77
	s_cmpk_gt_i32 s6, 0x7ff
	s_cselect_b64 s[8:9], -1, 0
	s_and_b64 vcc, exec, s[8:9]
	s_cbranch_vccnz .LBB0_1676
	s_ashr_i32 s7, s6, 31
	s_lshl_b64 s[14:15], s[6:7], 13
	v_lshl_add_u64 v[16:17], v[62:63], 0, s[14:15]
	v_lshl_add_u64 v[22:23], v[16:17], 0, v[56:57]
	v_lshl_add_u64 v[18:19], v[64:65], 0, s[14:15]
	v_lshl_add_u64 v[20:21], v[66:67], 0, s[14:15]
	global_load_dwordx4 v[0:3], v[22:23], off
	global_load_dwordx4 v[4:7], v[22:23], off offset:64
	global_load_dwordx4 v[8:11], v[18:19], off
	global_load_dwordx4 v[12:15], v[18:19], off offset:64
	global_load_dwordx2 v[70:71], v[20:21], off
	global_load_dwordx2 v[72:73], v[20:21], off offset:32
	v_mov_b32_e32 v69, v57
	v_lshl_add_u64 v[92:93], v[16:17], 0, v[68:69]
	global_load_dwordx4 v[16:19], v[92:93], off
	global_load_dwordx4 v[20:23], v[92:93], off offset:64
	s_waitcnt vmcnt(8)
	s_branch .Lp7_body
